# softmax: cross-half max combine moved to the rare rescale path, row sums kept as four running f32 pairs reduced once at loop exit; plus scalar-base GEMM LDS-DMA loads
# baseline (speedup 1.0000x reference)
.LBB0_227:
	s_lshl_b32 s4, s59, 11
	s_and_b32 s5, s4, 0x1000000
	s_lshl_b32 s4, s36, 4
	s_and_b32 s28, s4, 0x700
	v_lshl_or_b32 v96, v148, 1, s28
	v_or_b32_e32 v96, s5, v96
	v_mov_b32_e32 v97, v209
	s_lshl_b32 s21, s21, 9
	s_mov_b32 s65, 2
	s_add_i32 s66, s8, 2
	s_mov_b32 s4, 1
	v_lshl_add_u64 v[174:175], v[170:171], 0, v[96:97]
	v_subrev_u32_e32 v204, s21, v194
	s_add_i32 s33, s61, s8
	s_mov_b32 s87, 0
	s_movk_i32 s68, 0xff00
	v_mov_b64_e32 v[136:137], 0
	v_mov_b64_e32 v[138:139], 0
	v_mov_b64_e32 v[140:141], 0
	v_mov_b64_e32 v[142:143], 0
	s_waitcnt lgkmcnt(0)
	s_barrier
	s_and_b64 vcc, exec, s[16:17]
	s_cbranch_vccz .Latt_p_qk
	s_cmp_ge_u32 s65, s66
	s_cbranch_scc1 .LBB0_228
	s_mov_b32 s5, 0
	s_mov_b32 s28, 0x12800
	s_add_i32 m0, s5, s32
	s_nop 0
	global_load_lds_dwordx4 v128, s[80:81]
	s_add_i32 m0, m0, 0x2000
	s_nop 0
	global_load_lds_dwordx4 v129, s[80:81]
	s_cmp_eq_u32 s56, 0
	s_cbranch_scc0 .Ldk_p3
	s_add_i32 m0, s5, 0x4000
	s_nop 0
	global_load_lds_dwordx4 v132, s[80:81]

.Latt_b_nod:
	s_cmp_gt_i32 s86, s9
	s_cbranch_scc1 .Latt_b_bar
	v_max_f32_e32 v176, v96, v80
	v_max3_f32 v177, v81, v98, v82
	v_max3_f32 v176, v176, v97, v99
	v_max3_f32 v177, v177, v100, v84
	v_max3_f32 v176, v176, v83, v101
	v_max3_f32 v177, v177, v102, v86
	v_max3_f32 v176, v176, v85, v103
	v_max3_f32 v177, v177, v104, v88
	v_max3_f32 v176, v176, v87, v105
	v_max3_f32 v177, v177, v106, v90
	v_max3_f32 v176, v176, v89, v107
	v_max3_f32 v177, v177, v108, v92
	v_max3_f32 v176, v176, v91, v109
	v_max3_f32 v177, v177, v110, v94
	v_max3_f32 v176, v176, v93, v111
	v_max3_f32 v176, v176, v95, v177
	s_mov_b32 s4, 0x41000000
	v_cmp_lt_f32_e32 vcc, s4, v176
	s_cbranch_vccz .Latt_b_exp
	v_mov_b32_e32 v177, v176
	s_nop 1
	v_permlane32_swap_b32_e32 v176, v177
	v_max_f32_e32 v176, v176, v177
	v_max_f32_e32 v64, v176, v176
	v_max_f32_e32 v66, 0, v64
	v_exp_f32_e64 v176, -v66
	v_add_f32_e32 v173, v173, v66
	v_xor_b32_e32 v64, 0x80000000, v173
	v_pk_add_f32 v[96:97], v[96:97], v[66:67] op_sel_hi:[1,0] neg_lo:[0,1] neg_hi:[0,1]
	v_pk_add_f32 v[80:81], v[80:81], v[66:67] op_sel_hi:[1,0] neg_lo:[0,1] neg_hi:[0,1]
	v_pk_add_f32 v[98:99], v[98:99], v[66:67] op_sel_hi:[1,0] neg_lo:[0,1] neg_hi:[0,1]
	v_pk_add_f32 v[82:83], v[82:83], v[66:67] op_sel_hi:[1,0] neg_lo:[0,1] neg_hi:[0,1]
	v_pk_add_f32 v[100:101], v[100:101], v[66:67] op_sel_hi:[1,0] neg_lo:[0,1] neg_hi:[0,1]
	v_pk_add_f32 v[84:85], v[84:85], v[66:67] op_sel_hi:[1,0] neg_lo:[0,1] neg_hi:[0,1]
	v_pk_add_f32 v[102:103], v[102:103], v[66:67] op_sel_hi:[1,0] neg_lo:[0,1] neg_hi:[0,1]
	v_pk_add_f32 v[86:87], v[86:87], v[66:67] op_sel_hi:[1,0] neg_lo:[0,1] neg_hi:[0,1]
	v_pk_add_f32 v[104:105], v[104:105], v[66:67] op_sel_hi:[1,0] neg_lo:[0,1] neg_hi:[0,1]
	v_pk_add_f32 v[88:89], v[88:89], v[66:67] op_sel_hi:[1,0] neg_lo:[0,1] neg_hi:[0,1]
	v_pk_add_f32 v[106:107], v[106:107], v[66:67] op_sel_hi:[1,0] neg_lo:[0,1] neg_hi:[0,1]
	v_pk_add_f32 v[90:91], v[90:91], v[66:67] op_sel_hi:[1,0] neg_lo:[0,1] neg_hi:[0,1]
	v_pk_add_f32 v[108:109], v[108:109], v[66:67] op_sel_hi:[1,0] neg_lo:[0,1] neg_hi:[0,1]
	v_pk_add_f32 v[92:93], v[92:93], v[66:67] op_sel_hi:[1,0] neg_lo:[0,1] neg_hi:[0,1]
	v_pk_add_f32 v[110:111], v[110:111], v[66:67] op_sel_hi:[1,0] neg_lo:[0,1] neg_hi:[0,1]
	v_pk_add_f32 v[94:95], v[94:95], v[66:67] op_sel_hi:[1,0] neg_lo:[0,1] neg_hi:[0,1]
	v_mov_b32_e32 v65, v64
	v_mov_b32_e32 v66, v64
	v_mov_b32_e32 v67, v64
	v_mov_b32_e32 v68, v64
	v_mov_b32_e32 v69, v64
	v_mov_b32_e32 v70, v64
	v_mov_b32_e32 v71, v64
	v_mov_b32_e32 v72, v64
	v_mov_b32_e32 v73, v64
	v_mov_b32_e32 v74, v64
	v_mov_b32_e32 v75, v64
	v_mov_b32_e32 v76, v64
	v_mov_b32_e32 v77, v64
	v_mov_b32_e32 v78, v64
	v_mov_b32_e32 v79, v64
	v_pk_mul_f32 v[46:47], v[46:47], v[176:177] op_sel_hi:[1,0]
	v_pk_mul_f32 v[44:45], v[44:45], v[176:177] op_sel_hi:[1,0]
	v_pk_mul_f32 v[42:43], v[42:43], v[176:177] op_sel_hi:[1,0]
	v_pk_mul_f32 v[40:41], v[40:41], v[176:177] op_sel_hi:[1,0]
	v_pk_mul_f32 v[38:39], v[38:39], v[176:177] op_sel_hi:[1,0]
	v_pk_mul_f32 v[36:37], v[36:37], v[176:177] op_sel_hi:[1,0]
	v_pk_mul_f32 v[34:35], v[34:35], v[176:177] op_sel_hi:[1,0]
	v_pk_mul_f32 v[32:33], v[32:33], v[176:177] op_sel_hi:[1,0]
	v_pk_mul_f32 v[30:31], v[30:31], v[176:177] op_sel_hi:[1,0]
	v_pk_mul_f32 v[28:29], v[28:29], v[176:177] op_sel_hi:[1,0]
	v_pk_mul_f32 v[26:27], v[26:27], v[176:177] op_sel_hi:[1,0]
	v_pk_mul_f32 v[24:25], v[24:25], v[176:177] op_sel_hi:[1,0]
	v_pk_mul_f32 v[22:23], v[22:23], v[176:177] op_sel_hi:[1,0]
	v_pk_mul_f32 v[20:21], v[20:21], v[176:177] op_sel_hi:[1,0]
	v_pk_mul_f32 v[18:19], v[18:19], v[176:177] op_sel_hi:[1,0]
	v_pk_mul_f32 v[16:17], v[16:17], v[176:177] op_sel_hi:[1,0]
	v_pk_mul_f32 v[14:15], v[14:15], v[176:177] op_sel_hi:[1,0]
	v_pk_mul_f32 v[12:13], v[12:13], v[176:177] op_sel_hi:[1,0]
	v_pk_mul_f32 v[10:11], v[10:11], v[176:177] op_sel_hi:[1,0]
	v_pk_mul_f32 v[8:9], v[8:9], v[176:177] op_sel_hi:[1,0]
	v_pk_mul_f32 v[6:7], v[6:7], v[176:177] op_sel_hi:[1,0]
	v_pk_mul_f32 v[4:5], v[4:5], v[176:177] op_sel_hi:[1,0]
	v_pk_mul_f32 v[2:3], v[2:3], v[176:177] op_sel_hi:[1,0]
	v_pk_mul_f32 v[0:1], v[0:1], v[176:177] op_sel_hi:[1,0]
	v_pk_mul_f32 v[62:63], v[62:63], v[176:177] op_sel_hi:[1,0]
	v_pk_mul_f32 v[60:61], v[60:61], v[176:177] op_sel_hi:[1,0]
	v_pk_mul_f32 v[58:59], v[58:59], v[176:177] op_sel_hi:[1,0]
	v_pk_mul_f32 v[56:57], v[56:57], v[176:177] op_sel_hi:[1,0]
	v_pk_mul_f32 v[54:55], v[54:55], v[176:177] op_sel_hi:[1,0]
	v_pk_mul_f32 v[52:53], v[52:53], v[176:177] op_sel_hi:[1,0]
	v_pk_mul_f32 v[50:51], v[50:51], v[176:177] op_sel_hi:[1,0]
	v_pk_mul_f32 v[48:49], v[48:49], v[176:177] op_sel_hi:[1,0]
	v_mul_f32_e32 v172, v172, v176
	v_pk_mul_f32 v[136:137], v[136:137], v[176:177] op_sel_hi:[1,0]
	v_pk_mul_f32 v[138:139], v[138:139], v[176:177] op_sel_hi:[1,0]
	v_pk_mul_f32 v[140:141], v[140:141], v[176:177] op_sel_hi:[1,0]
	v_pk_mul_f32 v[142:143], v[142:143], v[176:177] op_sel_hi:[1,0]
.Latt_b_exp:
	v_exp_f32_e32 v96, v96
	v_exp_f32_e32 v97, v97
	v_exp_f32_e32 v176, v80
	v_exp_f32_e32 v177, v81
	v_exp_f32_e32 v98, v98
	v_exp_f32_e32 v99, v99
	v_exp_f32_e32 v178, v82
	v_exp_f32_e32 v179, v83
	v_exp_f32_e32 v100, v100
	v_exp_f32_e32 v101, v101
	v_exp_f32_e32 v180, v84
	v_exp_f32_e32 v181, v85
	v_exp_f32_e32 v102, v102
	v_exp_f32_e32 v103, v103
	v_exp_f32_e32 v182, v86
	v_exp_f32_e32 v183, v87
	v_exp_f32_e32 v104, v104
	v_exp_f32_e32 v105, v105
	v_exp_f32_e32 v184, v88
	v_exp_f32_e32 v185, v89
	v_exp_f32_e32 v106, v106
	v_exp_f32_e32 v107, v107
	v_exp_f32_e32 v186, v90
	v_exp_f32_e32 v187, v91
	v_exp_f32_e32 v108, v108
	v_exp_f32_e32 v109, v109
	v_exp_f32_e32 v188, v92
	v_exp_f32_e32 v189, v93
	v_exp_f32_e32 v110, v110
	v_exp_f32_e32 v111, v111
	v_exp_f32_e32 v190, v94
	v_exp_f32_e32 v191, v95
	v_cvt_pk_bf16_f32 v80, v96, v97
	v_cvt_pk_bf16_f32 v81, v98, v99
	v_cvt_pk_bf16_f32 v82, v100, v101
	v_cvt_pk_bf16_f32 v83, v102, v103
	v_cvt_pk_bf16_f32 v84, v104, v105
	v_cvt_pk_bf16_f32 v85, v106, v107
	v_cvt_pk_bf16_f32 v86, v108, v109
	v_cvt_pk_bf16_f32 v87, v110, v111
	v_cvt_pk_bf16_f32 v88, v176, v177
	v_cvt_pk_bf16_f32 v89, v178, v179
	v_cvt_pk_bf16_f32 v90, v180, v181
	v_cvt_pk_bf16_f32 v91, v182, v183
	v_cvt_pk_bf16_f32 v92, v184, v185
	v_cvt_pk_bf16_f32 v93, v186, v187
	v_cvt_pk_bf16_f32 v94, v188, v189
	v_cvt_pk_bf16_f32 v95, v190, v191
	v_pk_add_f32 v[96:97], v[96:97], v[100:101]
	v_pk_add_f32 v[98:99], v[98:99], v[102:103]
	v_pk_add_f32 v[176:177], v[176:177], v[180:181]
	v_pk_add_f32 v[178:179], v[178:179], v[182:183]
	v_pk_add_f32 v[96:97], v[96:97], v[104:105]
	v_pk_add_f32 v[98:99], v[98:99], v[106:107]
	v_pk_add_f32 v[176:177], v[176:177], v[184:185]
	v_pk_add_f32 v[178:179], v[178:179], v[186:187]
	v_pk_add_f32 v[96:97], v[96:97], v[108:109]
	v_pk_add_f32 v[98:99], v[98:99], v[110:111]
	v_pk_add_f32 v[176:177], v[176:177], v[188:189]
	v_pk_add_f32 v[178:179], v[178:179], v[190:191]
	v_pk_add_f32 v[136:137], v[136:137], v[96:97]
	v_pk_add_f32 v[138:139], v[138:139], v[98:99]
	v_pk_add_f32 v[140:141], v[140:141], v[176:177]
	v_pk_add_f32 v[142:143], v[142:143], v[178:179]

.Latt_a_nod:
	s_nop 9
	v_max_f32_e32 v176, v96, v80
	v_max3_f32 v177, v81, v98, v82
	v_max3_f32 v176, v176, v97, v99
	v_max3_f32 v177, v177, v100, v84
	v_max3_f32 v176, v176, v83, v101
	v_max3_f32 v177, v177, v102, v86
	v_max3_f32 v176, v176, v85, v103
	v_max3_f32 v177, v177, v104, v88
	v_max3_f32 v176, v176, v87, v105
	v_max3_f32 v177, v177, v106, v90
	v_max3_f32 v176, v176, v89, v107
	v_max3_f32 v177, v177, v108, v92
	v_max3_f32 v176, v176, v91, v109
	v_max3_f32 v177, v177, v110, v94
	v_max3_f32 v176, v176, v93, v111
	v_max3_f32 v176, v176, v95, v177
	s_mov_b32 s4, 0x41000000
	v_cmp_lt_f32_e32 vcc, s4, v176
	s_cbranch_vccz .Latt_a_exp
	v_mov_b32_e32 v177, v176
	s_nop 1
	v_permlane32_swap_b32_e32 v176, v177
	v_max_f32_e32 v176, v176, v177
	v_max_f32_e32 v64, v176, v176
	v_max_f32_e32 v66, 0, v64
	v_exp_f32_e64 v176, -v66
	v_add_f32_e32 v173, v173, v66
	v_xor_b32_e32 v64, 0x80000000, v173
	v_pk_add_f32 v[96:97], v[96:97], v[66:67] op_sel_hi:[1,0] neg_lo:[0,1] neg_hi:[0,1]
	v_pk_add_f32 v[80:81], v[80:81], v[66:67] op_sel_hi:[1,0] neg_lo:[0,1] neg_hi:[0,1]
	v_pk_add_f32 v[98:99], v[98:99], v[66:67] op_sel_hi:[1,0] neg_lo:[0,1] neg_hi:[0,1]
	v_pk_add_f32 v[82:83], v[82:83], v[66:67] op_sel_hi:[1,0] neg_lo:[0,1] neg_hi:[0,1]
	v_pk_add_f32 v[100:101], v[100:101], v[66:67] op_sel_hi:[1,0] neg_lo:[0,1] neg_hi:[0,1]
	v_pk_add_f32 v[84:85], v[84:85], v[66:67] op_sel_hi:[1,0] neg_lo:[0,1] neg_hi:[0,1]
	v_pk_add_f32 v[102:103], v[102:103], v[66:67] op_sel_hi:[1,0] neg_lo:[0,1] neg_hi:[0,1]
	v_pk_add_f32 v[86:87], v[86:87], v[66:67] op_sel_hi:[1,0] neg_lo:[0,1] neg_hi:[0,1]
	v_pk_add_f32 v[104:105], v[104:105], v[66:67] op_sel_hi:[1,0] neg_lo:[0,1] neg_hi:[0,1]
	v_pk_add_f32 v[88:89], v[88:89], v[66:67] op_sel_hi:[1,0] neg_lo:[0,1] neg_hi:[0,1]
	v_pk_add_f32 v[106:107], v[106:107], v[66:67] op_sel_hi:[1,0] neg_lo:[0,1] neg_hi:[0,1]
	v_pk_add_f32 v[90:91], v[90:91], v[66:67] op_sel_hi:[1,0] neg_lo:[0,1] neg_hi:[0,1]
	v_pk_add_f32 v[108:109], v[108:109], v[66:67] op_sel_hi:[1,0] neg_lo:[0,1] neg_hi:[0,1]
	v_pk_add_f32 v[92:93], v[92:93], v[66:67] op_sel_hi:[1,0] neg_lo:[0,1] neg_hi:[0,1]
	v_pk_add_f32 v[110:111], v[110:111], v[66:67] op_sel_hi:[1,0] neg_lo:[0,1] neg_hi:[0,1]
	v_pk_add_f32 v[94:95], v[94:95], v[66:67] op_sel_hi:[1,0] neg_lo:[0,1] neg_hi:[0,1]
	v_mov_b32_e32 v65, v64
	v_mov_b32_e32 v66, v64
	v_mov_b32_e32 v67, v64
	v_mov_b32_e32 v68, v64
	v_mov_b32_e32 v69, v64
	v_mov_b32_e32 v70, v64
	v_mov_b32_e32 v71, v64
	v_mov_b32_e32 v72, v64
	v_mov_b32_e32 v73, v64
	v_mov_b32_e32 v74, v64
	v_mov_b32_e32 v75, v64
	v_mov_b32_e32 v76, v64
	v_mov_b32_e32 v77, v64
	v_mov_b32_e32 v78, v64
	v_mov_b32_e32 v79, v64
	v_pk_mul_f32 v[46:47], v[46:47], v[176:177] op_sel_hi:[1,0]
	v_pk_mul_f32 v[44:45], v[44:45], v[176:177] op_sel_hi:[1,0]
	v_pk_mul_f32 v[42:43], v[42:43], v[176:177] op_sel_hi:[1,0]
	v_pk_mul_f32 v[40:41], v[40:41], v[176:177] op_sel_hi:[1,0]
	v_pk_mul_f32 v[38:39], v[38:39], v[176:177] op_sel_hi:[1,0]
	v_pk_mul_f32 v[36:37], v[36:37], v[176:177] op_sel_hi:[1,0]
	v_pk_mul_f32 v[34:35], v[34:35], v[176:177] op_sel_hi:[1,0]
	v_pk_mul_f32 v[32:33], v[32:33], v[176:177] op_sel_hi:[1,0]
	v_pk_mul_f32 v[30:31], v[30:31], v[176:177] op_sel_hi:[1,0]
	v_pk_mul_f32 v[28:29], v[28:29], v[176:177] op_sel_hi:[1,0]
	v_pk_mul_f32 v[26:27], v[26:27], v[176:177] op_sel_hi:[1,0]
	v_pk_mul_f32 v[24:25], v[24:25], v[176:177] op_sel_hi:[1,0]
	v_pk_mul_f32 v[22:23], v[22:23], v[176:177] op_sel_hi:[1,0]
	v_pk_mul_f32 v[20:21], v[20:21], v[176:177] op_sel_hi:[1,0]
	v_pk_mul_f32 v[18:19], v[18:19], v[176:177] op_sel_hi:[1,0]
	v_pk_mul_f32 v[16:17], v[16:17], v[176:177] op_sel_hi:[1,0]
	v_pk_mul_f32 v[14:15], v[14:15], v[176:177] op_sel_hi:[1,0]
	v_pk_mul_f32 v[12:13], v[12:13], v[176:177] op_sel_hi:[1,0]
	v_pk_mul_f32 v[10:11], v[10:11], v[176:177] op_sel_hi:[1,0]
	v_pk_mul_f32 v[8:9], v[8:9], v[176:177] op_sel_hi:[1,0]
	v_pk_mul_f32 v[6:7], v[6:7], v[176:177] op_sel_hi:[1,0]
	v_pk_mul_f32 v[4:5], v[4:5], v[176:177] op_sel_hi:[1,0]
	v_pk_mul_f32 v[2:3], v[2:3], v[176:177] op_sel_hi:[1,0]
	v_pk_mul_f32 v[0:1], v[0:1], v[176:177] op_sel_hi:[1,0]
	v_pk_mul_f32 v[62:63], v[62:63], v[176:177] op_sel_hi:[1,0]
	v_pk_mul_f32 v[60:61], v[60:61], v[176:177] op_sel_hi:[1,0]
	v_pk_mul_f32 v[58:59], v[58:59], v[176:177] op_sel_hi:[1,0]
	v_pk_mul_f32 v[56:57], v[56:57], v[176:177] op_sel_hi:[1,0]
	v_pk_mul_f32 v[54:55], v[54:55], v[176:177] op_sel_hi:[1,0]
	v_pk_mul_f32 v[52:53], v[52:53], v[176:177] op_sel_hi:[1,0]
	v_pk_mul_f32 v[50:51], v[50:51], v[176:177] op_sel_hi:[1,0]
	v_pk_mul_f32 v[48:49], v[48:49], v[176:177] op_sel_hi:[1,0]
	v_mul_f32_e32 v172, v172, v176
	v_pk_mul_f32 v[136:137], v[136:137], v[176:177] op_sel_hi:[1,0]
	v_pk_mul_f32 v[138:139], v[138:139], v[176:177] op_sel_hi:[1,0]
	v_pk_mul_f32 v[140:141], v[140:141], v[176:177] op_sel_hi:[1,0]
	v_pk_mul_f32 v[142:143], v[142:143], v[176:177] op_sel_hi:[1,0]

.LBB0_243:
	v_pk_add_f32 v[136:137], v[136:137], v[138:139]
	v_pk_add_f32 v[140:141], v[140:141], v[142:143]
	s_nop 0
	v_pk_add_f32 v[136:137], v[136:137], v[140:141]
	s_nop 0
	v_add_f32_e32 v136, v136, v137
	v_add_f32_e32 v172, v172, v136

	s_and_b64 vcc, exec, s[16:17]
	s_cbranch_vccz .LBB0_245
	s_mul_i32 s4, s69, 0x5000
	v_add_u32_e32 v96, s4, v165
	ds_read_b64_tr_b16 v[64:65], v96 offset:34816
	ds_read_b64_tr_b16 v[66:67], v96 offset:37376
	ds_read_b64_tr_b16 v[68:69], v96 offset:39936
	ds_read_b64_tr_b16 v[70:71], v96 offset:42496
	ds_read_b64_tr_b16 v[72:73], v96 offset:45056
	ds_read_b64_tr_b16 v[74:75], v96 offset:47616
	ds_read_b64_tr_b16 v[76:77], v96 offset:50176
	ds_read_b64_tr_b16 v[78:79], v96 offset:52736
	s_setprio 1
	s_waitcnt lgkmcnt(6)
	v_mfma_f32_32x32x16_bf16 v[32:47], v[64:67], v[80:83], v[32:47]
	s_setprio 0
	ds_read_b64_tr_b16 v[64:65], v96 offset:34880
	ds_read_b64_tr_b16 v[66:67], v96 offset:37440
	s_setprio 1
	s_waitcnt lgkmcnt(6)
	v_mfma_f32_32x32x16_bf16 v[32:47], v[68:71], v[84:87], v[32:47]
	s_setprio 0
	ds_read_b64_tr_b16 v[68:69], v96 offset:40000
	ds_read_b64_tr_b16 v[70:71], v96 offset:42560
	s_setprio 1
	s_waitcnt lgkmcnt(6)
	v_mfma_f32_32x32x16_bf16 v[32:47], v[72:75], v[88:91], v[32:47]
	s_setprio 0
	ds_read_b64_tr_b16 v[72:73], v96 offset:45120
	ds_read_b64_tr_b16 v[74:75], v96 offset:47680
	s_setprio 1
	s_waitcnt lgkmcnt(6)
	v_mfma_f32_32x32x16_bf16 v[32:47], v[76:79], v[92:95], v[32:47]
	s_setprio 0
	ds_read_b64_tr_b16 v[76:77], v96 offset:50240
	ds_read_b64_tr_b16 v[78:79], v96 offset:52800
	s_setprio 1
	s_waitcnt lgkmcnt(6)
	v_mfma_f32_32x32x16_bf16 v[16:31], v[64:67], v[80:83], v[16:31]
	s_setprio 0
	ds_read_b64_tr_b16 v[64:65], v96 offset:34944
	ds_read_b64_tr_b16 v[66:67], v96 offset:37504
	s_setprio 1
	s_waitcnt lgkmcnt(6)
	v_mfma_f32_32x32x16_bf16 v[16:31], v[68:71], v[84:87], v[16:31]
	s_setprio 0
	ds_read_b64_tr_b16 v[68:69], v96 offset:40064
	ds_read_b64_tr_b16 v[70:71], v96 offset:42624
	s_setprio 1
	s_waitcnt lgkmcnt(6)
	v_mfma_f32_32x32x16_bf16 v[16:31], v[72:75], v[88:91], v[16:31]
	s_setprio 0
	ds_read_b64_tr_b16 v[72:73], v96 offset:45184
	ds_read_b64_tr_b16 v[74:75], v96 offset:47744
	s_setprio 1
	s_waitcnt lgkmcnt(6)
	v_mfma_f32_32x32x16_bf16 v[16:31], v[76:79], v[92:95], v[16:31]
	s_setprio 0
	ds_read_b64_tr_b16 v[76:77], v96 offset:50304
	ds_read_b64_tr_b16 v[78:79], v96 offset:52864
	s_setprio 1
	s_waitcnt lgkmcnt(6)
	v_mfma_f32_32x32x16_bf16 v[0:15], v[64:67], v[80:83], v[0:15]
	s_setprio 0
	ds_read_b64_tr_b16 v[64:65], v96 offset:35008
	ds_read_b64_tr_b16 v[66:67], v96 offset:37568
	s_setprio 1
	s_waitcnt lgkmcnt(6)
	v_mfma_f32_32x32x16_bf16 v[0:15], v[68:71], v[84:87], v[0:15]
	s_setprio 0
	ds_read_b64_tr_b16 v[68:69], v96 offset:40128
	ds_read_b64_tr_b16 v[70:71], v96 offset:42688
	s_setprio 1
	s_waitcnt lgkmcnt(6)
	v_mfma_f32_32x32x16_bf16 v[0:15], v[72:75], v[88:91], v[0:15]
	s_setprio 0
	ds_read_b64_tr_b16 v[72:73], v96 offset:45248
	ds_read_b64_tr_b16 v[74:75], v96 offset:47808
	s_setprio 1
	s_waitcnt lgkmcnt(6)
	v_mfma_f32_32x32x16_bf16 v[0:15], v[76:79], v[92:95], v[0:15]
	s_setprio 0
	ds_read_b64_tr_b16 v[76:77], v96 offset:50368
	ds_read_b64_tr_b16 v[78:79], v96 offset:52928
	s_setprio 1
	s_waitcnt lgkmcnt(6)
	v_mfma_f32_32x32x16_bf16 v[48:63], v[64:67], v[80:83], v[48:63]
	s_setprio 0
	s_setprio 1
	s_waitcnt lgkmcnt(4)
	v_mfma_f32_32x32x16_bf16 v[48:63], v[68:71], v[84:87], v[48:63]
	s_setprio 0
	s_setprio 1
	s_waitcnt lgkmcnt(2)
	v_mfma_f32_32x32x16_bf16 v[48:63], v[72:75], v[88:91], v[48:63]
	s_setprio 0
	s_setprio 1
	s_waitcnt lgkmcnt(0)
	v_mfma_f32_32x32x16_bf16 v[48:63], v[76:79], v[92:95], v[48:63]
	s_setprio 0
